# P1 adaLN table loop unrolled x2 (two columns' 35 loads issued together, 4 load round trips instead of 8) on top of mid-arrival flush
# speedup vs baseline: 1.0106x; 1.0106x over previous
; __device__ __forceinline__ void p1_rows(const Params& P, LAS unsigned char* lds, int G) {
;     ...
;     for (int idx = tid; idx < 2 * DM; idx += NTHREADS) { const int b = idx >> 11, col = idx & (DM - 1);
;         float sh = P.b_ada[col], sc = P.b_ada[DM + col];
;         for (int ks = 0; ks < KS_ADA; ++ks) { sh += adap[(size_t)(ks * 2 + b) * NADA + col]; sc += adap[(size_t)(ks * 2 + b) * NADA + DM + col]; }
;         TA[idx] = P.g_pre_mix[col] * (1.0f + sc); TC[idx] = sh; }
.LBB0_156:
	s_or_b64 exec, exec, s[4:5]
	v_mov_b32_e32 v8, v168
	s_movk_i32 s4, 0x1000
	s_waitcnt lgkmcnt(0)
	s_barrier
	s_nop 0
	v_cmp_gt_i32_e32 vcc, s4, v8
	s_and_saveexec_b64 s[4:5], vcc
	s_cbranch_execz .LBB0_161
	s_mov_b64 s[6:7], 0
	v_mov_b32_e32 v1, 0
	s_movk_i32 s10, 0xbff
	v_mov_b32_e32 v3, v8
	v_mov_b32_e32 v9, v8
; __device__ __forceinline__ void p1_rows(const Params& P, LAS unsigned char* lds, int G) {
;     ...
;     for (int idx = tid; idx < 2 * DM; idx += NTHREADS) { const int b = idx >> 11, col = idx & (DM - 1);
;         float sh = P.b_ada[col], sc = P.b_ada[DM + col];
;         for (int ks = 0; ks < KS_ADA; ++ks) { sh += adap[(size_t)(ks * 2 + b) * NADA + col]; sc += adap[(size_t)(ks * 2 + b) * NADA + DM + col]; }
;         TA[idx] = P.g_pre_mix[col] * (1.0f + sc); TC[idx] = sh; }
.LBB0_158:
	v_and_b32_e32 v2, 0x7ff, v9
	v_ashrrev_i32_e32 v6, 11, v9
	v_lshlrev_b32_e32 v0, 2, v2
	v_mul_i32_i24_e32 v6, 0xc000, v6
	s_add_u32 s8, s68, 0x2000
	s_addc_u32 s9, s69, 0
	v_lshl_or_b32 v6, v2, 2, v6
	global_load_dword v4, v0, s[68:69]
	global_load_dword v50, v0, s[68:69] offset:2048
	global_load_dword v5, v0, s[8:9]
	global_load_dword v51, v0, s[8:9] offset:2048
	global_load_dword v44, v0, s[70:71]
	global_load_dword v52, v0, s[70:71] offset:2048
	s_add_u32 s8, s58, 0x0
	s_addc_u32 s9, s59, 0
	global_load_dword v12, v6, s[8:9]
	global_load_dword v60, v6, s[8:9] offset:2048
	s_add_u32 s8, s58, 0x2000
	s_addc_u32 s9, s59, 0
	global_load_dword v13, v6, s[8:9]
	global_load_dword v61, v6, s[8:9] offset:2048
	s_add_u32 s8, s58, 0x18000
	s_addc_u32 s9, s59, 0
	global_load_dword v14, v6, s[8:9]
	global_load_dword v62, v6, s[8:9] offset:2048
	s_add_u32 s8, s58, 0x1a000
	s_addc_u32 s9, s59, 0
	global_load_dword v15, v6, s[8:9]
	global_load_dword v63, v6, s[8:9] offset:2048
	s_add_u32 s8, s58, 0x30000
	s_addc_u32 s9, s59, 0
	global_load_dword v16, v6, s[8:9]
	global_load_dword v64, v6, s[8:9] offset:2048
	s_add_u32 s8, s58, 0x32000
	s_addc_u32 s9, s59, 0
	global_load_dword v17, v6, s[8:9]
	global_load_dword v65, v6, s[8:9] offset:2048
	s_add_u32 s8, s58, 0x48000
	s_addc_u32 s9, s59, 0
	global_load_dword v18, v6, s[8:9]
	global_load_dword v66, v6, s[8:9] offset:2048
	s_add_u32 s8, s58, 0x4a000
	s_addc_u32 s9, s59, 0
	global_load_dword v19, v6, s[8:9]
	global_load_dword v67, v6, s[8:9] offset:2048
	s_add_u32 s8, s58, 0x60000
	s_addc_u32 s9, s59, 0
	global_load_dword v20, v6, s[8:9]
	global_load_dword v68, v6, s[8:9] offset:2048
	s_add_u32 s8, s58, 0x62000
	s_addc_u32 s9, s59, 0
	global_load_dword v21, v6, s[8:9]
	global_load_dword v69, v6, s[8:9] offset:2048
	s_add_u32 s8, s58, 0x78000
	s_addc_u32 s9, s59, 0
	global_load_dword v22, v6, s[8:9]
	global_load_dword v70, v6, s[8:9] offset:2048
	s_add_u32 s8, s58, 0x7a000
	s_addc_u32 s9, s59, 0
	global_load_dword v23, v6, s[8:9]
	global_load_dword v71, v6, s[8:9] offset:2048
	s_add_u32 s8, s58, 0x90000
	s_addc_u32 s9, s59, 0
	global_load_dword v24, v6, s[8:9]
	global_load_dword v72, v6, s[8:9] offset:2048
	s_add_u32 s8, s58, 0x92000
	s_addc_u32 s9, s59, 0
	global_load_dword v25, v6, s[8:9]
	global_load_dword v73, v6, s[8:9] offset:2048
	s_add_u32 s8, s58, 0xa8000
	s_addc_u32 s9, s59, 0
	global_load_dword v26, v6, s[8:9]
	global_load_dword v74, v6, s[8:9] offset:2048
	s_add_u32 s8, s58, 0xaa000
	s_addc_u32 s9, s59, 0
	global_load_dword v27, v6, s[8:9]
	global_load_dword v75, v6, s[8:9] offset:2048
	s_add_u32 s8, s58, 0xc0000
	s_addc_u32 s9, s59, 0
	global_load_dword v28, v6, s[8:9]
	global_load_dword v76, v6, s[8:9] offset:2048
	s_add_u32 s8, s58, 0xc2000
	s_addc_u32 s9, s59, 0
	global_load_dword v29, v6, s[8:9]
	global_load_dword v77, v6, s[8:9] offset:2048
	s_add_u32 s8, s58, 0xd8000
	s_addc_u32 s9, s59, 0
	global_load_dword v30, v6, s[8:9]
	global_load_dword v78, v6, s[8:9] offset:2048
	s_add_u32 s8, s58, 0xda000
	s_addc_u32 s9, s59, 0
	global_load_dword v31, v6, s[8:9]
	global_load_dword v79, v6, s[8:9] offset:2048
	s_add_u32 s8, s58, 0xf0000
	s_addc_u32 s9, s59, 0
	global_load_dword v32, v6, s[8:9]
	global_load_dword v80, v6, s[8:9] offset:2048
	s_add_u32 s8, s58, 0xf2000
	s_addc_u32 s9, s59, 0
	global_load_dword v33, v6, s[8:9]
	global_load_dword v81, v6, s[8:9] offset:2048
	s_add_u32 s8, s58, 0x108000
	s_addc_u32 s9, s59, 0
	global_load_dword v34, v6, s[8:9]
	global_load_dword v82, v6, s[8:9] offset:2048
	s_add_u32 s8, s58, 0x10a000
	s_addc_u32 s9, s59, 0
	global_load_dword v35, v6, s[8:9]
	global_load_dword v83, v6, s[8:9] offset:2048
	s_add_u32 s8, s58, 0x120000
	s_addc_u32 s9, s59, 0
	global_load_dword v36, v6, s[8:9]
	global_load_dword v84, v6, s[8:9] offset:2048
	s_add_u32 s8, s58, 0x122000
	s_addc_u32 s9, s59, 0
	global_load_dword v37, v6, s[8:9]
	global_load_dword v85, v6, s[8:9] offset:2048
	s_add_u32 s8, s58, 0x138000
	s_addc_u32 s9, s59, 0
	global_load_dword v38, v6, s[8:9]
	global_load_dword v86, v6, s[8:9] offset:2048
	s_add_u32 s8, s58, 0x13a000
	s_addc_u32 s9, s59, 0
	global_load_dword v39, v6, s[8:9]
	global_load_dword v87, v6, s[8:9] offset:2048
	s_add_u32 s8, s58, 0x150000
	s_addc_u32 s9, s59, 0
	s_waitcnt vmcnt(61)
	global_load_dword v40, v6, s[8:9]
	global_load_dword v88, v6, s[8:9] offset:2048
	s_add_u32 s8, s58, 0x152000
	s_addc_u32 s9, s59, 0
	s_waitcnt vmcnt(61)
	global_load_dword v41, v6, s[8:9]
	global_load_dword v89, v6, s[8:9] offset:2048
	s_add_u32 s8, s58, 0x168000
	s_addc_u32 s9, s59, 0
	s_waitcnt vmcnt(61)
	global_load_dword v42, v6, s[8:9]
	global_load_dword v90, v6, s[8:9] offset:2048
	s_add_u32 s8, s58, 0x16a000
	s_addc_u32 s9, s59, 0
	s_waitcnt vmcnt(61)
	global_load_dword v43, v6, s[8:9]
	global_load_dword v91, v6, s[8:9] offset:2048
	v_add_u32_e32 v6, 0x400, v9
	v_cmp_lt_i32_e32 vcc, s10, v9
	v_lshl_add_u32 v7, v9, 2, 0
	v_add_u16_e32 v3, 0x400, v3
	s_or_b64 s[6:7], vcc, s[6:7]
	v_mov_b32_e32 v9, v6
	s_waitcnt vmcnt(60)
	v_pk_add_f32 v[4:5], v[4:5], v[12:13]
	v_pk_add_f32 v[50:51], v[50:51], v[60:61]
	s_waitcnt vmcnt(56)
	v_pk_add_f32 v[4:5], v[4:5], v[14:15]
	v_pk_add_f32 v[50:51], v[50:51], v[62:63]
	s_waitcnt vmcnt(52)
	v_pk_add_f32 v[4:5], v[4:5], v[16:17]
	v_pk_add_f32 v[50:51], v[50:51], v[64:65]
	s_waitcnt vmcnt(48)
	v_pk_add_f32 v[4:5], v[4:5], v[18:19]
	v_pk_add_f32 v[50:51], v[50:51], v[66:67]
	s_waitcnt vmcnt(44)
	v_pk_add_f32 v[4:5], v[4:5], v[20:21]
	v_pk_add_f32 v[50:51], v[50:51], v[68:69]
	s_waitcnt vmcnt(40)
	v_pk_add_f32 v[4:5], v[4:5], v[22:23]
	v_pk_add_f32 v[50:51], v[50:51], v[70:71]
	s_waitcnt vmcnt(36)
	v_pk_add_f32 v[4:5], v[4:5], v[24:25]
	v_pk_add_f32 v[50:51], v[50:51], v[72:73]
	s_waitcnt vmcnt(32)
	v_pk_add_f32 v[4:5], v[4:5], v[26:27]
	v_pk_add_f32 v[50:51], v[50:51], v[74:75]
	s_waitcnt vmcnt(28)
	v_pk_add_f32 v[4:5], v[4:5], v[28:29]
	v_pk_add_f32 v[50:51], v[50:51], v[76:77]
	s_waitcnt vmcnt(24)
	v_pk_add_f32 v[4:5], v[4:5], v[30:31]
	v_pk_add_f32 v[50:51], v[50:51], v[78:79]
	s_waitcnt vmcnt(20)
	v_pk_add_f32 v[4:5], v[4:5], v[32:33]
	v_pk_add_f32 v[50:51], v[50:51], v[80:81]
	s_waitcnt vmcnt(16)
	v_pk_add_f32 v[4:5], v[4:5], v[34:35]
	v_pk_add_f32 v[50:51], v[50:51], v[82:83]
	s_waitcnt vmcnt(12)
	v_pk_add_f32 v[4:5], v[4:5], v[36:37]
	v_pk_add_f32 v[50:51], v[50:51], v[84:85]
	s_waitcnt vmcnt(8)
	v_pk_add_f32 v[4:5], v[4:5], v[38:39]
	v_pk_add_f32 v[50:51], v[50:51], v[86:87]
	s_waitcnt vmcnt(4)
	v_pk_add_f32 v[4:5], v[4:5], v[40:41]
	v_pk_add_f32 v[50:51], v[50:51], v[88:89]
	s_waitcnt vmcnt(0)
	v_pk_add_f32 v[4:5], v[4:5], v[42:43]
	v_pk_add_f32 v[50:51], v[50:51], v[90:91]
	v_add_f32_e32 v2, 1.0, v5
	v_add_f32_e32 v53, 1.0, v51
	s_nop 0
	v_mul_f32_e32 v0, v2, v44
	v_mul_f32_e32 v54, v53, v52
	ds_write2st64_b32 v7, v0, v4 offset1:64
	ds_write2st64_b32 v7, v54, v50 offset0:8 offset1:72
	s_andn2_b64 exec, exec, s[6:7]
	s_cbranch_execnz .LBB0_158
